# seams: the middle local arriver of each XCD starts an early L2 write-back so the last arriver's flush has less to write
# baseline (speedup 1.0000x reference)
; __device__ __forceinline__ unsigned xb_ld(unsigned* p)              { return __hip_atomic_load(p, __ATOMIC_RELAXED, __HIP_MEMORY_SCOPE_AGENT); }
; __device__ __forceinline__ unsigned xb_add(unsigned* p, unsigned v) { return __hip_atomic_fetch_add(p, v, __ATOMIC_RELAXED, __HIP_MEMORY_SCOPE_AGENT); }
; #define XB_SPIN(cond, bar) do { unsigned _sp = 0; while (cond) { __builtin_amdgcn_s_sleep(1); \
;     if ((++_sp & 255u) == 0u) { if (xb_ld(&(bar)[XB_TMO])) break; if (_sp > XB_SPIN_CAP) { atomicAdd(&(bar)[XB_TMO], 1u); break; } } } } while (0)
; __device__ __forceinline__ void xcd_barrier(const XcdBarrier& b) {
;     ...
;         const unsigned old = xb_add(&bar[XB_XSUB(b.x)], 1u);
;         const unsigned gen = old / nloc;
;         if (old + 1u == (gen + 1u) * nloc) {
;             __builtin_amdgcn_fence(__ATOMIC_RELEASE, "agent");
;             asm volatile("s_waitcnt vmcnt(0)" ::: "memory");
;             const unsigned og = xb_add(&bar[XB_TOP], 1u);
;             const unsigned tg = og / nx;
;             if (og + 1u == (tg + 1u) * nx) xb_add(&bar[XB_TOPGEN], 1u);
;             else XB_SPIN(xb_ld(&bar[XB_TOPGEN]) == tg, bar);
.Lg0_arrive:
	s_lshl_b32 s15, s10, 8
	s_add_i32 s15, s15, 0x8000
	v_mov_b32_e32 v0, s15
	v_mov_b32_e32 v1, 1
	global_atomic_add v1, v0, v1, s[4:5] sc0
	s_waitcnt vmcnt(0)
	v_readfirstlane_b32 s16, v1
	s_add_i32 s16, s16, 1
	s_cmp_lg_u32 s16, s14
	s_cbranch_scc1 .Lg0_mid
	buffer_wbl2 sc1
	s_waitcnt vmcnt(0)
	v_mov_b32_e32 v0, 0x9000
	v_mov_b32_e32 v1, s14
	global_atomic_add v0, v1, s[4:5]
	s_branch .Lg0_wait
.Lg0_mid:
	s_lshr_b32 s11, s14, 1
	s_sub_i32 s11, s14, s11
	s_cmp_lg_u32 s16, s11
	s_cbranch_scc1 .Lg0_wait
	buffer_wbl2 sc1

; __device__ __forceinline__ unsigned xb_ld(unsigned* p)              { return __hip_atomic_load(p, __ATOMIC_RELAXED, __HIP_MEMORY_SCOPE_AGENT); }
; __device__ __forceinline__ unsigned xb_add(unsigned* p, unsigned v) { return __hip_atomic_fetch_add(p, v, __ATOMIC_RELAXED, __HIP_MEMORY_SCOPE_AGENT); }
; #define XB_SPIN(cond, bar) do { unsigned _sp = 0; while (cond) { __builtin_amdgcn_s_sleep(1); \
;     if ((++_sp & 255u) == 0u) { if (xb_ld(&(bar)[XB_TMO])) break; if (_sp > XB_SPIN_CAP) { atomicAdd(&(bar)[XB_TMO], 1u); break; } } } } while (0)
; __device__ __forceinline__ void xcd_barrier(const XcdBarrier& b) {
;     ...
;         const unsigned old = xb_add(&bar[XB_XSUB(b.x)], 1u);
;         const unsigned gen = old / nloc;
;         if (old + 1u == (gen + 1u) * nloc) {
;             __builtin_amdgcn_fence(__ATOMIC_RELEASE, "agent");
;             asm volatile("s_waitcnt vmcnt(0)" ::: "memory");
;             const unsigned og = xb_add(&bar[XB_TOP], 1u);
;             const unsigned tg = og / nx;
;             if (og + 1u == (tg + 1u) * nx) xb_add(&bar[XB_TOPGEN], 1u);
;             else XB_SPIN(xb_ld(&bar[XB_TOPGEN]) == tg, bar);
.LBB0_466:
	s_or_b32 s10, s58, 2
	s_cmp_ge_i32 s10, s19
	s_cbranch_scc1 .LBB0_520
	v_mov_b32_e32 v0, s42
	ds_read_b64 v[2:3], v0
	s_getreg_b32 s6, hwreg(HW_REG_XCC_ID, 0, 4)
	s_waitcnt vmcnt(0)
	s_waitcnt vmcnt(0) lgkmcnt(0)
	s_barrier
	v_readfirstlane_b32 s5, v3
	v_readfirstlane_b32 s4, v2
	s_and_saveexec_b64 s[0:1], s[78:79]
	s_cbranch_execz .LBB0_519
	v_mov_b32_e32 v0, 0x250d0
	ds_read_b64 v[6:7], v0
	v_mov_b32_e32 v0, 0x25100
	ds_read2_b32 v[8:9], v0 offset1:2
	s_getreg_b32 s12, hwreg(HW_REG_XCC_ID, 0, 4)
	s_waitcnt vmcnt(0) lgkmcnt(0)
	v_readfirstlane_b32 s40, v6
	v_readfirstlane_b32 s41, v7
	v_readfirstlane_b32 s14, v8
	v_readfirstlane_b32 s17, v9
	s_add_u32 s40, s40, 0x1e600000
	s_addc_u32 s41, s41, 0
	s_and_b32 s12, s12, 15
	s_add_i32 s17, s17, 1
	v_mov_b32_e32 v8, s17
	ds_write_b32 v0, v8 offset:8
	s_mul_i32 s28, s17, s14
	s_mul_i32 s30, s17, s34
	s_lshl_b32 s31, s12, 8
	s_add_i32 s31, s31, 0x8000
	v_mov_b32_e32 v0, s31
	v_mov_b32_e32 v6, 1
	global_atomic_add v6, v0, v6, s[40:41] sc0
	s_waitcnt vmcnt(0)
	v_readfirstlane_b32 s31, v6
	s_add_i32 s31, s31, 1
	s_cmp_lg_u32 s31, s28
	s_cbranch_scc1 .Lsb0_mid
	buffer_wbl2 sc1
	s_waitcnt vmcnt(0)
	v_mov_b32_e32 v0, 0x9000
	v_mov_b32_e32 v6, s14
	global_atomic_add v0, v6, s[40:41]
	s_branch .Lsb0_wait
.Lsb0_mid:
	s_lshr_b32 s44, s14, 1
	s_sub_i32 s44, s28, s44
	s_cmp_lg_u32 s31, s44
	s_cbranch_scc1 .Lsb0_wait
	buffer_wbl2 sc1

; __device__ __forceinline__ unsigned xb_ld(unsigned* p)              { return __hip_atomic_load(p, __ATOMIC_RELAXED, __HIP_MEMORY_SCOPE_AGENT); }
; __device__ __forceinline__ unsigned xb_add(unsigned* p, unsigned v) { return __hip_atomic_fetch_add(p, v, __ATOMIC_RELAXED, __HIP_MEMORY_SCOPE_AGENT); }
; #define XB_SPIN(cond, bar) do { unsigned _sp = 0; while (cond) { __builtin_amdgcn_s_sleep(1); \
;     if ((++_sp & 255u) == 0u) { if (xb_ld(&(bar)[XB_TMO])) break; if (_sp > XB_SPIN_CAP) { atomicAdd(&(bar)[XB_TMO], 1u); break; } } } } while (0)
; __device__ __forceinline__ void xcd_barrier(const XcdBarrier& b) {
;     ...
;         const unsigned old = xb_add(&bar[XB_XSUB(b.x)], 1u);
;         const unsigned gen = old / nloc;
;         if (old + 1u == (gen + 1u) * nloc) {
;             __builtin_amdgcn_fence(__ATOMIC_RELEASE, "agent");
;             asm volatile("s_waitcnt vmcnt(0)" ::: "memory");
;             const unsigned og = xb_add(&bar[XB_TOP], 1u);
;             const unsigned tg = og / nx;
;             if (og + 1u == (tg + 1u) * nx) xb_add(&bar[XB_TOPGEN], 1u);
;             else XB_SPIN(xb_ld(&bar[XB_TOPGEN]) == tg, bar);
.LBB0_699:
	s_or_b32 s10, s58, 3
	s_cmp_ge_i32 s10, s19
	s_cbranch_scc1 .LBB0_711
	v_mov_b32_e32 v0, s42
	ds_read_b64 v[2:3], v0
	s_getreg_b32 s6, hwreg(HW_REG_XCC_ID, 0, 4)
	s_waitcnt vmcnt(0)
	s_waitcnt vmcnt(0) lgkmcnt(0)
	s_barrier
	v_readfirstlane_b32 s5, v3
	v_readfirstlane_b32 s4, v2
	s_and_saveexec_b64 s[0:1], s[78:79]
	s_movk_i32 s37, 0xb00
	s_movk_i32 s43, 0x51
	s_mul_i32 s48, s34, 3
	s_mul_hi_i32 s49, s34, 3
	v_readlane_b32 s50, v255, 33
	s_cbranch_execz .LBB0_753
	v_mov_b32_e32 v0, 0x250d0
	ds_read_b64 v[6:7], v0
	v_mov_b32_e32 v0, 0x25100
	ds_read2_b32 v[8:9], v0 offset1:2
	s_getreg_b32 s12, hwreg(HW_REG_XCC_ID, 0, 4)
	s_waitcnt vmcnt(0) lgkmcnt(0)
	v_readfirstlane_b32 s40, v6
	v_readfirstlane_b32 s41, v7
	v_readfirstlane_b32 s14, v8
	v_readfirstlane_b32 s17, v9
	s_add_u32 s40, s40, 0x1e600000
	s_addc_u32 s41, s41, 0
	s_and_b32 s12, s12, 15
	s_add_i32 s17, s17, 1
	v_mov_b32_e32 v8, s17
	ds_write_b32 v0, v8 offset:8
	s_mul_i32 s28, s17, s14
	s_mul_i32 s30, s17, s34
	s_lshl_b32 s31, s12, 8
	s_add_i32 s31, s31, 0x8000
	v_mov_b32_e32 v0, s31
	v_mov_b32_e32 v6, 1
	global_atomic_add v6, v0, v6, s[40:41] sc0
	s_waitcnt vmcnt(0)
	v_readfirstlane_b32 s31, v6
	s_add_i32 s31, s31, 1
	s_cmp_lg_u32 s31, s28
	s_cbranch_scc1 .LsbM_mid
	buffer_wbl2 sc1
	s_waitcnt vmcnt(0)
	v_mov_b32_e32 v0, 0x9000
	v_mov_b32_e32 v6, s14
	global_atomic_add v0, v6, s[40:41]
	s_branch .LsbM_wait

; __device__ __forceinline__ unsigned xb_ld(unsigned* p)              { return __hip_atomic_load(p, __ATOMIC_RELAXED, __HIP_MEMORY_SCOPE_AGENT); }
; __device__ __forceinline__ unsigned xb_add(unsigned* p, unsigned v) { return __hip_atomic_fetch_add(p, v, __ATOMIC_RELAXED, __HIP_MEMORY_SCOPE_AGENT); }
; #define XB_SPIN(cond, bar) do { unsigned _sp = 0; while (cond) { __builtin_amdgcn_s_sleep(1); \
;     if ((++_sp & 255u) == 0u) { if (xb_ld(&(bar)[XB_TMO])) break; if (_sp > XB_SPIN_CAP) { atomicAdd(&(bar)[XB_TMO], 1u); break; } } } } while (0)
; __device__ __forceinline__ void xcd_barrier(const XcdBarrier& b) {
;     ...
;         const unsigned old = xb_add(&bar[XB_XSUB(b.x)], 1u);
;         const unsigned gen = old / nloc;
;         if (old + 1u == (gen + 1u) * nloc) {
;             __builtin_amdgcn_fence(__ATOMIC_RELEASE, "agent");
;             asm volatile("s_waitcnt vmcnt(0)" ::: "memory");
;             const unsigned og = xb_add(&bar[XB_TOP], 1u);
;             const unsigned tg = og / nx;
;             if (og + 1u == (tg + 1u) * nx) xb_add(&bar[XB_TOPGEN], 1u);
;             else XB_SPIN(xb_ld(&bar[XB_TOPGEN]) == tg, bar);
.LBB0_793:
	s_or_b32 s4, s58, 4
	s_cmp_ge_i32 s4, s19
	s_cbranch_scc1 .LBB0_847
	v_mov_b32_e32 v0, s42
	ds_read_b64 v[2:3], v0
	s_getreg_b32 s5, hwreg(HW_REG_XCC_ID, 0, 4)
	s_waitcnt vmcnt(0)
	s_waitcnt vmcnt(0) lgkmcnt(0)
	s_barrier
	v_readfirstlane_b32 s7, v3
	v_readfirstlane_b32 s6, v2
	s_and_saveexec_b64 s[0:1], s[78:79]
	s_cbranch_execz .LBB0_846
	v_mov_b32_e32 v0, 0x250d0
	ds_read_b64 v[6:7], v0
	v_mov_b32_e32 v0, 0x25100
	ds_read2_b32 v[8:9], v0 offset1:2
	s_getreg_b32 s12, hwreg(HW_REG_XCC_ID, 0, 4)
	s_waitcnt vmcnt(0) lgkmcnt(0)
	v_readfirstlane_b32 s40, v6
	v_readfirstlane_b32 s41, v7
	v_readfirstlane_b32 s14, v8
	v_readfirstlane_b32 s17, v9
	s_add_u32 s40, s40, 0x1e600000
	s_addc_u32 s41, s41, 0
	s_and_b32 s12, s12, 15
	s_add_i32 s17, s17, 1
	v_mov_b32_e32 v8, s17
	ds_write_b32 v0, v8 offset:8
	s_mul_i32 s28, s17, s14
	s_mul_i32 s30, s17, s34
	s_lshl_b32 s31, s12, 8
	s_add_i32 s31, s31, 0x8000
	v_mov_b32_e32 v0, s31
	v_mov_b32_e32 v6, 1
	global_atomic_add v6, v0, v6, s[40:41] sc0
	s_waitcnt vmcnt(0)
	v_readfirstlane_b32 s31, v6
	s_add_i32 s31, s31, 1
	s_cmp_lg_u32 s31, s28
	s_cbranch_scc1 .Lsb2_mid
	buffer_wbl2 sc1
	s_waitcnt vmcnt(0)
	v_mov_b32_e32 v0, 0x9000
	v_mov_b32_e32 v6, s14
	global_atomic_add v0, v6, s[40:41]
	s_branch .Lsb2_wait

; __device__ __forceinline__ unsigned xb_ld(unsigned* p)              { return __hip_atomic_load(p, __ATOMIC_RELAXED, __HIP_MEMORY_SCOPE_AGENT); }
; __device__ __forceinline__ unsigned xb_add(unsigned* p, unsigned v) { return __hip_atomic_fetch_add(p, v, __ATOMIC_RELAXED, __HIP_MEMORY_SCOPE_AGENT); }
; #define XB_SPIN(cond, bar) do { unsigned _sp = 0; while (cond) { __builtin_amdgcn_s_sleep(1); \
;     if ((++_sp & 255u) == 0u) { if (xb_ld(&(bar)[XB_TMO])) break; if (_sp > XB_SPIN_CAP) { atomicAdd(&(bar)[XB_TMO], 1u); break; } } } } while (0)
; __device__ __forceinline__ void xcd_barrier(const XcdBarrier& b) {
;     ...
;         const unsigned old = xb_add(&bar[XB_XSUB(b.x)], 1u);
;         const unsigned gen = old / nloc;
;         if (old + 1u == (gen + 1u) * nloc) {
;             __builtin_amdgcn_fence(__ATOMIC_RELEASE, "agent");
;             asm volatile("s_waitcnt vmcnt(0)" ::: "memory");
;             const unsigned og = xb_add(&bar[XB_TOP], 1u);
;             const unsigned tg = og / nx;
;             if (og + 1u == (tg + 1u) * nx) xb_add(&bar[XB_TOPGEN], 1u);
;             else XB_SPIN(xb_ld(&bar[XB_TOPGEN]) == tg, bar);
.LBB0_909:
	s_or_b32 s4, s58, 5
	s_cmp_ge_i32 s4, s19
	s_cbranch_scc1 .LBB0_963
	v_mov_b32_e32 v0, s42
	ds_read_b64 v[2:3], v0
	s_getreg_b32 s5, hwreg(HW_REG_XCC_ID, 0, 4)
	s_waitcnt vmcnt(0)
	s_waitcnt vmcnt(0) lgkmcnt(0)
	s_barrier
	v_readfirstlane_b32 s7, v3
	v_readfirstlane_b32 s6, v2
	s_and_saveexec_b64 s[0:1], s[78:79]
	s_cbranch_execz .LBB0_962
	v_mov_b32_e32 v0, 0x250d0
	ds_read_b64 v[6:7], v0
	v_mov_b32_e32 v0, 0x25100
	ds_read2_b32 v[8:9], v0 offset1:2
	s_getreg_b32 s12, hwreg(HW_REG_XCC_ID, 0, 4)
	s_waitcnt vmcnt(0) lgkmcnt(0)
	v_readfirstlane_b32 s40, v6
	v_readfirstlane_b32 s41, v7
	v_readfirstlane_b32 s14, v8
	v_readfirstlane_b32 s17, v9
	s_add_u32 s40, s40, 0x1e600000
	s_addc_u32 s41, s41, 0
	s_and_b32 s12, s12, 15
	s_add_i32 s17, s17, 1
	v_mov_b32_e32 v8, s17
	ds_write_b32 v0, v8 offset:8
	s_mul_i32 s28, s17, s14
	s_mul_i32 s30, s17, s34
	s_lshl_b32 s31, s12, 8
	s_add_i32 s31, s31, 0x8000
	v_mov_b32_e32 v0, s31
	v_mov_b32_e32 v6, 1
	global_atomic_add v6, v0, v6, s[40:41] sc0
	s_waitcnt vmcnt(0)
	v_readfirstlane_b32 s31, v6
	s_add_i32 s31, s31, 1
	s_cmp_lg_u32 s31, s28
	s_cbranch_scc1 .Lsb3_mid
	buffer_wbl2 sc1
	s_waitcnt vmcnt(0)
	v_mov_b32_e32 v0, 0x9000
	v_mov_b32_e32 v6, s14
	global_atomic_add v0, v6, s[40:41]
	s_branch .Lsb3_wait

; __device__ __forceinline__ unsigned xb_ld(unsigned* p)              { return __hip_atomic_load(p, __ATOMIC_RELAXED, __HIP_MEMORY_SCOPE_AGENT); }
; __device__ __forceinline__ unsigned xb_add(unsigned* p, unsigned v) { return __hip_atomic_fetch_add(p, v, __ATOMIC_RELAXED, __HIP_MEMORY_SCOPE_AGENT); }
; #define XB_SPIN(cond, bar) do { unsigned _sp = 0; while (cond) { __builtin_amdgcn_s_sleep(1); \
;     if ((++_sp & 255u) == 0u) { if (xb_ld(&(bar)[XB_TMO])) break; if (_sp > XB_SPIN_CAP) { atomicAdd(&(bar)[XB_TMO], 1u); break; } } } } while (0)
; __device__ __forceinline__ void xcd_barrier(const XcdBarrier& b) {
;     ...
;         const unsigned old = xb_add(&bar[XB_XSUB(b.x)], 1u);
;         const unsigned gen = old / nloc;
;         if (old + 1u == (gen + 1u) * nloc) {
;             __builtin_amdgcn_fence(__ATOMIC_RELEASE, "agent");
;             asm volatile("s_waitcnt vmcnt(0)" ::: "memory");
;             const unsigned og = xb_add(&bar[XB_TOP], 1u);
;             const unsigned tg = og / nx;
;             if (og + 1u == (tg + 1u) * nx) xb_add(&bar[XB_TOPGEN], 1u);
;             else XB_SPIN(xb_ld(&bar[XB_TOPGEN]) == tg, bar);
.LBB0_994:
	v_mov_b32_e32 v0, s42
	ds_read_b64 v[2:3], v0
	s_getreg_b32 s5, hwreg(HW_REG_XCC_ID, 0, 4)
	s_waitcnt vmcnt(0)
	s_waitcnt vmcnt(0) lgkmcnt(0)
	s_barrier
	v_readfirstlane_b32 s7, v3
	v_readfirstlane_b32 s6, v2
	s_and_saveexec_b64 s[0:1], s[78:79]
	s_cbranch_execz .LBB0_1046
	v_mov_b32_e32 v0, 0x250d0
	ds_read_b64 v[6:7], v0
	v_mov_b32_e32 v0, 0x25100
	ds_read2_b32 v[8:9], v0 offset1:2
	s_getreg_b32 s12, hwreg(HW_REG_XCC_ID, 0, 4)
	s_waitcnt vmcnt(0) lgkmcnt(0)
	v_readfirstlane_b32 s40, v6
	v_readfirstlane_b32 s41, v7
	v_readfirstlane_b32 s14, v8
	v_readfirstlane_b32 s17, v9
	s_add_u32 s40, s40, 0x1e600000
	s_addc_u32 s41, s41, 0
	s_and_b32 s12, s12, 15
	s_add_i32 s17, s17, 1
	v_mov_b32_e32 v8, s17
	ds_write_b32 v0, v8 offset:8
	s_mul_i32 s28, s17, s14
	s_mul_i32 s30, s17, s34
	s_lshl_b32 s31, s12, 8
	s_add_i32 s31, s31, 0x8000
	v_mov_b32_e32 v0, s31
	v_mov_b32_e32 v6, 1
	global_atomic_add v6, v0, v6, s[40:41] sc0
	s_waitcnt vmcnt(0)
	v_readfirstlane_b32 s31, v6
	s_add_i32 s31, s31, 1
	s_cmp_lg_u32 s31, s28
	s_cbranch_scc1 .Lsb4_mid
	buffer_wbl2 sc1
	s_waitcnt vmcnt(0)
	v_mov_b32_e32 v0, 0x9000
	v_mov_b32_e32 v6, s14
	global_atomic_add v0, v6, s[40:41]
	s_branch .Lsb4_wait

; __device__ __forceinline__ unsigned xb_ld(unsigned* p)              { return __hip_atomic_load(p, __ATOMIC_RELAXED, __HIP_MEMORY_SCOPE_AGENT); }
; __device__ __forceinline__ unsigned xb_add(unsigned* p, unsigned v) { return __hip_atomic_fetch_add(p, v, __ATOMIC_RELAXED, __HIP_MEMORY_SCOPE_AGENT); }
; #define XB_SPIN(cond, bar) do { unsigned _sp = 0; while (cond) { __builtin_amdgcn_s_sleep(1); \
;     if ((++_sp & 255u) == 0u) { if (xb_ld(&(bar)[XB_TMO])) break; if (_sp > XB_SPIN_CAP) { atomicAdd(&(bar)[XB_TMO], 1u); break; } } } } while (0)
; __device__ __forceinline__ void xcd_barrier(const XcdBarrier& b) {
;     ...
;         const unsigned old = xb_add(&bar[XB_XSUB(b.x)], 1u);
;         const unsigned gen = old / nloc;
;         if (old + 1u == (gen + 1u) * nloc) {
;             __builtin_amdgcn_fence(__ATOMIC_RELEASE, "agent");
;             asm volatile("s_waitcnt vmcnt(0)" ::: "memory");
;             const unsigned og = xb_add(&bar[XB_TOP], 1u);
;             const unsigned tg = og / nx;
;             if (og + 1u == (tg + 1u) * nx) xb_add(&bar[XB_TOPGEN], 1u);
;             else XB_SPIN(xb_ld(&bar[XB_TOPGEN]) == tg, bar);
.LBB0_1086:
	s_or_b32 s4, s58, 7
	s_cmp_ge_i32 s4, s19
	s_cbranch_scc1 .LBB0_1140
	v_mov_b32_e32 v0, s42
	ds_read_b64 v[2:3], v0
	s_getreg_b32 s5, hwreg(HW_REG_XCC_ID, 0, 4)
	s_waitcnt vmcnt(0)
	s_waitcnt vmcnt(0) lgkmcnt(0)
	s_barrier
	v_readfirstlane_b32 s7, v3
	v_readfirstlane_b32 s6, v2
	s_and_saveexec_b64 s[0:1], s[78:79]
	s_cbranch_execz .LBB0_1139
	v_mov_b32_e32 v0, 0x250d0
	ds_read_b64 v[6:7], v0
	v_mov_b32_e32 v0, 0x25100
	ds_read2_b32 v[8:9], v0 offset1:2
	s_getreg_b32 s12, hwreg(HW_REG_XCC_ID, 0, 4)
	s_waitcnt vmcnt(0) lgkmcnt(0)
	v_readfirstlane_b32 s40, v6
	v_readfirstlane_b32 s41, v7
	v_readfirstlane_b32 s14, v8
	v_readfirstlane_b32 s17, v9
	s_add_u32 s40, s40, 0x1e600000
	s_addc_u32 s41, s41, 0
	s_and_b32 s12, s12, 15
	s_add_i32 s17, s17, 1
	v_mov_b32_e32 v8, s17
	ds_write_b32 v0, v8 offset:8
	s_mul_i32 s28, s17, s14
	s_mul_i32 s30, s17, s34
	s_lshl_b32 s31, s12, 8
	s_add_i32 s31, s31, 0x8000
	v_mov_b32_e32 v0, s31
	v_mov_b32_e32 v6, 1
	global_atomic_add v6, v0, v6, s[40:41] sc0
	s_waitcnt vmcnt(0)
	v_readfirstlane_b32 s31, v6
	s_add_i32 s31, s31, 1
	s_cmp_lg_u32 s31, s28
	s_cbranch_scc1 .Lsb5_mid
	buffer_wbl2 sc1
	s_waitcnt vmcnt(0)
	v_mov_b32_e32 v0, 0x9000
	v_mov_b32_e32 v6, s14
	global_atomic_add v0, v6, s[40:41]
	s_branch .Lsb5_wait

; __device__ __forceinline__ unsigned xb_ld(unsigned* p)              { return __hip_atomic_load(p, __ATOMIC_RELAXED, __HIP_MEMORY_SCOPE_AGENT); }
; __device__ __forceinline__ unsigned xb_add(unsigned* p, unsigned v) { return __hip_atomic_fetch_add(p, v, __ATOMIC_RELAXED, __HIP_MEMORY_SCOPE_AGENT); }
; #define XB_SPIN(cond, bar) do { unsigned _sp = 0; while (cond) { __builtin_amdgcn_s_sleep(1); \
;     if ((++_sp & 255u) == 0u) { if (xb_ld(&(bar)[XB_TMO])) break; if (_sp > XB_SPIN_CAP) { atomicAdd(&(bar)[XB_TMO], 1u); break; } } } } while (0)
; __device__ __forceinline__ void xcd_barrier(const XcdBarrier& b) {
;     ...
;         const unsigned old = xb_add(&bar[XB_XSUB(b.x)], 1u);
;         const unsigned gen = old / nloc;
;         if (old + 1u == (gen + 1u) * nloc) {
;             __builtin_amdgcn_fence(__ATOMIC_RELEASE, "agent");
;             asm volatile("s_waitcnt vmcnt(0)" ::: "memory");
;             const unsigned og = xb_add(&bar[XB_TOP], 1u);
;             const unsigned tg = og / nx;
;             if (og + 1u == (tg + 1u) * nx) xb_add(&bar[XB_TOPGEN], 1u);
;             else XB_SPIN(xb_ld(&bar[XB_TOPGEN]) == tg, bar);
.LBB0_1204:
	s_add_i32 s4, s58, 8
	s_cmp_ge_i32 s4, s19
	s_cbranch_scc1 .LBB0_1258
	v_mov_b32_e32 v0, s42
	ds_read_b64 v[2:3], v0
	s_getreg_b32 s5, hwreg(HW_REG_XCC_ID, 0, 4)
	s_waitcnt vmcnt(0)
	s_waitcnt lgkmcnt(0)
	s_barrier
	v_readfirstlane_b32 s7, v3
	v_readfirstlane_b32 s6, v2
	s_and_saveexec_b64 s[0:1], s[78:79]
	s_cbranch_execz .LBB0_1257
	v_mov_b32_e32 v0, 0x250d0
	ds_read_b64 v[6:7], v0
	v_mov_b32_e32 v0, 0x25100
	ds_read2_b32 v[8:9], v0 offset1:2
	s_getreg_b32 s12, hwreg(HW_REG_XCC_ID, 0, 4)
	s_waitcnt vmcnt(0) lgkmcnt(0)
	v_readfirstlane_b32 s40, v6
	v_readfirstlane_b32 s41, v7
	v_readfirstlane_b32 s14, v8
	v_readfirstlane_b32 s17, v9
	s_add_u32 s40, s40, 0x1e600000
	s_addc_u32 s41, s41, 0
	s_and_b32 s12, s12, 15
	s_add_i32 s17, s17, 1
	v_mov_b32_e32 v8, s17
	ds_write_b32 v0, v8 offset:8
	s_mul_i32 s28, s17, s14
	s_mul_i32 s30, s17, s34
	s_lshl_b32 s31, s12, 8
	s_add_i32 s31, s31, 0x8000
	v_mov_b32_e32 v0, s31
	v_mov_b32_e32 v6, 1
	global_atomic_add v6, v0, v6, s[40:41] sc0
	s_waitcnt vmcnt(0)
	v_readfirstlane_b32 s31, v6
	s_add_i32 s31, s31, 1
	s_cmp_lg_u32 s31, s28
	s_cbranch_scc1 .Lsb6_mid
	buffer_wbl2 sc1
	s_waitcnt vmcnt(0)
	v_mov_b32_e32 v0, 0x9000
	v_mov_b32_e32 v6, s14
	global_atomic_add v0, v6, s[40:41]
	s_branch .Lsb6_wait

; __device__ __forceinline__ unsigned xb_ld(unsigned* p)              { return __hip_atomic_load(p, __ATOMIC_RELAXED, __HIP_MEMORY_SCOPE_AGENT); }
; __device__ __forceinline__ unsigned xb_add(unsigned* p, unsigned v) { return __hip_atomic_fetch_add(p, v, __ATOMIC_RELAXED, __HIP_MEMORY_SCOPE_AGENT); }
; #define XB_SPIN(cond, bar) do { unsigned _sp = 0; while (cond) { __builtin_amdgcn_s_sleep(1); \
;     if ((++_sp & 255u) == 0u) { if (xb_ld(&(bar)[XB_TMO])) break; if (_sp > XB_SPIN_CAP) { atomicAdd(&(bar)[XB_TMO], 1u); break; } } } } while (0)
; __device__ __forceinline__ void xcd_barrier(const XcdBarrier& b) {
;     ...
;         const unsigned old = xb_add(&bar[XB_XSUB(b.x)], 1u);
;         const unsigned gen = old / nloc;
;         if (old + 1u == (gen + 1u) * nloc) {
;             __builtin_amdgcn_fence(__ATOMIC_RELEASE, "agent");
;             asm volatile("s_waitcnt vmcnt(0)" ::: "memory");
;             const unsigned og = xb_add(&bar[XB_TOP], 1u);
;             const unsigned tg = og / nx;
;             if (og + 1u == (tg + 1u) * nx) xb_add(&bar[XB_TOPGEN], 1u);
;             else XB_SPIN(xb_ld(&bar[XB_TOPGEN]) == tg, bar);
.LBB0_1366:
	v_mov_b32_e32 v0, 0x250d0
	ds_read_b64 v[6:7], v0
	v_mov_b32_e32 v0, 0x25100
	ds_read2_b32 v[8:9], v0 offset1:2
	s_getreg_b32 s12, hwreg(HW_REG_XCC_ID, 0, 4)
	s_waitcnt vmcnt(0) lgkmcnt(0)
	v_readfirstlane_b32 s40, v6
	v_readfirstlane_b32 s41, v7
	v_readfirstlane_b32 s14, v8
	v_readfirstlane_b32 s17, v9
	s_add_u32 s40, s40, 0x1e600000
	s_addc_u32 s41, s41, 0
	s_and_b32 s12, s12, 15
	s_add_i32 s17, s17, 1
	v_mov_b32_e32 v8, s17
	ds_write_b32 v0, v8 offset:8
	s_mul_i32 s28, s17, s14
	s_mul_i32 s30, s17, s34
	s_lshl_b32 s31, s12, 8
	s_add_i32 s31, s31, 0x8000
	v_mov_b32_e32 v0, s31
	v_mov_b32_e32 v6, 1
	global_atomic_add v6, v0, v6, s[40:41] sc0
	s_waitcnt vmcnt(0)
	v_readfirstlane_b32 s31, v6
	s_add_i32 s31, s31, 1
	s_cmp_lg_u32 s31, s28
	s_cbranch_scc1 .LsbL_mid
	buffer_wbl2 sc1
	s_waitcnt vmcnt(0)
	v_mov_b32_e32 v0, 0x9000
	v_mov_b32_e32 v6, s14
	global_atomic_add v0, v6, s[40:41]
	s_branch .LsbL_wait
